# NSA item setup de-serialisation: bias-table loads waited with a counted vmcnt after the Q/gate loads are issued (one exposed latency fewer per item)
# speedup vs baseline: 1.0060x; 1.0015x over previous
.LBB0_1274:
	s_mov_b64 s[12:13], -1
	s_and_b64 vcc, exec, s[10:11]
	s_cbranch_vccz .LBB0_1263
	s_lshl_b32 s6, s28, 2
	s_and_b32 s54, s6, 12
	s_load_dwordx2 s[6:7], s[58:59], 0x10
	v_add_u32_e32 v2, s54, v185
	v_ashrrev_i32_e32 v3, 31, v2
	s_waitcnt lgkmcnt(0)
	v_lshl_add_u64 v[2:3], v[2:3], 2, s[6:7]
	global_load_dword v251, v[2:3], off
	v_lshl_add_u64 v[2:3], v[150:151], 0, s[54:55]
	v_lshl_add_u64 v[2:3], v[2:3], 2, s[6:7]
	global_load_dword v252, v[2:3], off offset:1984
	ds_write2_b32 v189, v1, v1 offset1:2
	ds_write2_b32 v189, v1, v1 offset0:4 offset1:6
	ds_write2_b32 v189, v1, v1 offset0:8 offset1:10
	ds_write2_b32 v189, v1, v1 offset0:12 offset1:14
	ds_write2_b32 v189, v1, v1 offset0:16 offset1:18
	ds_write2_b32 v189, v1, v1 offset0:20 offset1:22
	ds_write2_b32 v189, v1, v1 offset0:24 offset1:26
	ds_write2_b32 v189, v1, v1 offset0:28 offset1:30
	ds_write2_b32 v189, v1, v1 offset0:32 offset1:34
	ds_write2_b32 v189, v1, v1 offset0:36 offset1:38
	ds_write2_b32 v189, v1, v1 offset0:40 offset1:42
	ds_write2_b32 v189, v1, v1 offset0:44 offset1:46
	ds_write2_b32 v189, v1, v1 offset0:48 offset1:50
	ds_write2_b32 v189, v1, v1 offset0:52 offset1:54
	ds_write2_b32 v189, v1, v1 offset0:56 offset1:58
	ds_write2_b32 v189, v1, v1 offset0:60 offset1:62
	s_and_saveexec_b64 s[10:11], s[8:9]
	ds_write_b32 v187, v1 offset:256
	s_or_b64 exec, exec, s[10:11]
	s_mov_b64 s[10:11], exec
	v_readlane_b32 s6, v254, 29
	v_readlane_b32 s7, v254, 30
	s_and_b64 s[6:7], s[10:11], s[6:7]
	s_mov_b64 exec, s[6:7]
	ds_write_b32 v188, v1
	s_or_b64 exec, exec, s[10:11]
	s_lshl_b32 s26, s27, 6
	s_add_i32 s26, s26, s69
	s_lshl_b32 s6, s28, 10
	v_or_b32_e32 v156, s26, v184
	s_and_b32 s6, s6, 0x7000
	s_mov_b32 s7, s55
	v_ashrrev_i32_e32 v157, 31, v156
	v_lshl_add_u64 v[154:155], s[6:7], 0, v[156:157]
	v_readlane_b32 s6, v254, 16
	v_readlane_b32 s7, v254, 17
	s_movk_i32 s11, 0xa00
	s_or_b32 s10, s54, s4
	v_mov_b64_e32 v[2:3], s[6:7]
	v_mad_u64_u32 v[2:3], s[6:7], v154, s11, v[2:3]
	v_mad_i32_i24 v3, v155, s11, v3
	s_lshl_b32 s54, s10, 7
	v_lshl_add_u64 v[4:5], v[2:3], 0, s[54:55]
	v_mov_b32_e32 v153, v1
	s_mul_i32 s54, s10, 6
	v_lshl_add_u64 v[4:5], v[4:5], 0, v[152:153]
	v_lshl_add_u64 v[2:3], v[2:3], 0, s[54:55]
	global_load_dwordx4 v[130:133], v[4:5], off
	global_load_dwordx4 v[134:137], v[4:5], off offset:32
	global_load_dwordx4 v[138:141], v[4:5], off offset:64
	global_load_dwordx4 v[142:145], v[4:5], off offset:96
	global_load_dword v0, v[2:3], off offset:2048
	s_waitcnt vmcnt(5)
	v_sub_f32_e32 v251, v251, v252
	v_mul_f32_e32 v251, 0x3fb8aa3b, v251
	ds_write_b32 v186, v251
	s_ashr_i32 s6, s27, 4
	s_min_i32 s6, s6, 3
	s_add_i32 s6, s6, 1
	s_and_b32 s29, s28, 31
	s_lshl_b64 s[6:7], -1, s6
	s_lshl_b32 s61, s10, 6
	s_not_b64 s[10:11], s[6:7]
	s_lshl_b32 s12, s29, 15
	s_add_u32 s12, s64, s12
	s_addc_u32 s13, s65, 0
	s_or_b32 s30, s29, 32
	s_lshl_b32 s14, s30, 15
	s_add_u32 s14, s64, s14
	s_addc_u32 s15, s65, 0
	s_ff1_i32_b64 s31, s[10:11]
	s_sub_u32 s10, -2, s6
	s_subb_u32 s11, 0x7fffffff, s7
	s_andn2_b64 s[10:11], s[10:11], s[6:7]
	s_mul_i32 s6, s31, s85
	s_mul_hi_u32 s7, s31, s84
	s_add_i32 s7, s7, s6
	s_mul_i32 s6, s31, s84
	s_lshl_b64 s[6:7], s[6:7], 7
	v_mov_b32_e32 v6, v149
	s_add_u32 s18, s12, s6
	s_addc_u32 s19, s13, s7
	s_add_u32 s16, s14, s6
	s_addc_u32 s17, s15, s7
	v_mov_b32_e32 v52, 0xf149f2ca
	v_mov_b32_e32 v53, 0
	s_mov_b32 s34, s31
	s_mov_b64 s[20:21], s[10:11]
	s_waitcnt vmcnt(0)
	v_lshlrev_b32_e32 v4, 16, v0
	v_and_b32_e32 v0, 0xffff0000, v0
	v_mul_f32_e32 v0, 0xbfb8aa3b, v0
	v_exp_f32_e32 v46, v0
	global_load_ushort v0, v[2:3], off offset:2052
	v_mul_f32_e32 v4, 0xbfb8aa3b, v4
	v_lshlrev_b32_e32 v2, 3, v6
	v_ashrrev_i32_e32 v7, 3, v6
	v_and_b32_e32 v2, 56, v2
	v_mad_u64_u32 v[2:3], s[6:7], v7, s84, v[2:3]
	v_mov_b32_e32 v3, v1
	v_lshlrev_b64 v[2:3], 1, v[2:3]
	v_exp_f32_e32 v157, v4
	v_lshl_add_u64 v[4:5], s[18:19], 0, v[2:3]
	global_load_dwordx4 v[34:37], v[4:5], off
	v_lshl_add_u64 v[4:5], s[16:17], 0, v[2:3]
	global_load_dwordx4 v[38:41], v[4:5], off
	s_movk_i32 s6, 0x90
	v_lshlrev_b32_e32 v4, 4, v6
	v_mul_lo_u32 v47, v7, s6
	v_and_b32_e32 v48, 0x70, v4
	v_lshl_add_u64 v[42:43], s[12:13], 0, v[2:3]
	v_lshl_add_u64 v[44:45], s[14:15], 0, v[2:3]
	v_and_b32_e32 v2, 31, v6
	v_lshrrev_b32_e32 v3, 1, v6
	v_add3_u32 v4, 0, v47, v48
	s_movk_i32 s6, 0xc0
	v_mul_u32_u24_e32 v2, 0x90, v2
	v_and_b32_e32 v3, 16, v3
	v_mul_lo_u32 v49, v7, s6
	v_add3_u32 v50, 0, v2, v3
	v_lshrrev_b32_e32 v2, 3, v6
	v_and_b32_e32 v51, 4, v2
	s_waitcnt vmcnt(2)
	v_lshlrev_b32_e32 v0, 16, v0
	v_mul_f32_e32 v0, 0xbfb8aa3b, v0
	v_exp_f32_e32 v153, v0
	v_subrev_u32_e32 v0, 31, v156
	v_ashrrev_i32_e32 v0, 4, v0
	v_min_i32_e32 v0, 0xfe, v0
	s_waitcnt vmcnt(1)
	ds_write_b128 v4, v[34:37]
	v_mad_u64_u32 v[4:5], s[6:7], v7, 48, v[4:5]
	s_mov_b32 s6, 0
	s_waitcnt vmcnt(0)
	ds_write_b128 v4, v[38:41] offset:9216
	s_waitcnt lgkmcnt(0)
	s_barrier
